# grid barrier: non-leader workgroups poll the global generation word directly instead of the per-XCD relay word (one polling hop less on release)
# speedup vs baseline: 1.0111x; 1.0009x over previous
.LBB0_155:
	s_or_b64 exec, exec, s[8:9]
	v_cvt_f32_u32_e32 v5, v2
	s_waitcnt vmcnt(0)
	v_readfirstlane_b32 s6, v4
	v_sub_u32_e32 v4, 0, v2
	v_rcp_iflag_f32_e32 v5, v5
	v_add_u32_e32 v6, s6, v1
	v_mul_f32_e32 v5, 0x4f7ffffe, v5
	v_cvt_u32_f32_e32 v5, v5
	v_mul_lo_u32 v1, v4, v5
	v_mul_hi_u32 v1, v5, v1
	v_add_u32_e32 v1, v5, v1
	v_mul_hi_u32 v1, v6, v1
	v_mul_lo_u32 v4, v1, v2
	v_sub_u32_e32 v4, v6, v4
	v_add_u32_e32 v5, 1, v1
	v_cmp_ge_u32_e32 vcc, v4, v2
	s_nop 1
	v_cndmask_b32_e32 v1, v1, v5, vcc
	v_sub_u32_e32 v5, v4, v2
	v_cndmask_b32_e32 v4, v4, v5, vcc
	v_add_u32_e32 v5, 1, v1
	v_cmp_ge_u32_e32 vcc, v4, v2
	v_add_u32_e32 v4, 1, v6
	s_nop 0
	v_cndmask_b32_e32 v1, v1, v5, vcc
	v_mul_lo_u32 v5, v2, v1
	v_add_u32_e32 v2, v5, v2
	v_cmp_ne_u32_e32 vcc, v4, v2
	s_and_saveexec_b64 s[6:7], vcc
	s_xor_b64 s[6:7], exec, s[6:7]
	s_cbranch_execz .LBB0_169
	s_waitcnt lgkmcnt(0)
	s_add_u32 s12, s2, 0x3783500
	s_addc_u32 s13, s3, 0
	global_load_dword v0, v3, s[12:13] sc1
	s_waitcnt vmcnt(0)
	v_cmp_eq_u32_e32 vcc, v0, v1
	s_and_saveexec_b64 s[8:9], vcc
	s_cbranch_execz .LBB0_168
	s_add_u32 s10, s2, 0x3780200
	s_addc_u32 s11, s3, 0
	s_mov_b32 s21, 1
	s_mov_b64 s[14:15], 0
	s_branch .LBB0_159

.LBB0_1177:
	s_or_b64 exec, exec, s[8:9]
	v_cvt_f32_u32_e32 v5, v2
	s_waitcnt vmcnt(0)
	v_readfirstlane_b32 s6, v4
	v_sub_u32_e32 v4, 0, v2
	v_rcp_iflag_f32_e32 v5, v5
	v_add_u32_e32 v6, s6, v1
	v_mul_f32_e32 v5, 0x4f7ffffe, v5
	v_cvt_u32_f32_e32 v5, v5
	v_mul_lo_u32 v1, v4, v5
	v_mul_hi_u32 v1, v5, v1
	v_add_u32_e32 v1, v5, v1
	v_mul_hi_u32 v1, v6, v1
	v_mul_lo_u32 v4, v1, v2
	v_sub_u32_e32 v4, v6, v4
	v_add_u32_e32 v5, 1, v1
	v_cmp_ge_u32_e32 vcc, v4, v2
	s_nop 1
	v_cndmask_b32_e32 v1, v1, v5, vcc
	v_sub_u32_e32 v5, v4, v2
	v_cndmask_b32_e32 v4, v4, v5, vcc
	v_add_u32_e32 v5, 1, v1
	v_cmp_ge_u32_e32 vcc, v4, v2
	v_add_u32_e32 v4, 1, v6
	s_nop 0
	v_cndmask_b32_e32 v1, v1, v5, vcc
	v_mul_lo_u32 v5, v2, v1
	v_add_u32_e32 v2, v5, v2
	v_cmp_ne_u32_e32 vcc, v4, v2
	s_and_saveexec_b64 s[6:7], vcc
	s_xor_b64 s[6:7], exec, s[6:7]
	s_cbranch_execz .LBB0_1191
	s_waitcnt lgkmcnt(0)
	s_add_u32 s12, s2, 0x3783500
	s_addc_u32 s13, s3, 0
	global_load_dword v0, v3, s[12:13] sc1
	s_waitcnt vmcnt(0)
	v_cmp_eq_u32_e32 vcc, v0, v1
	s_and_saveexec_b64 s[8:9], vcc
	s_cbranch_execz .LBB0_1190
	s_add_u32 s10, s2, 0x3780200
	s_addc_u32 s11, s3, 0
	s_mov_b32 s24, 1
	s_mov_b64 s[14:15], 0
	s_branch .LBB0_1181
